# MLA back-edge rotation part 2: late waves form the P.V(prev) V-fragment address in front of the tile barrier and branch straight to the reads
# baseline (speedup 1.0000x reference)
; DI void mla_block(const Params& p, LAS unsigned char* lds, int b, int hd, int qb, int tid) {
;     ...
;     for (int kt = 0; kt < ntiles; ++kt) {
;         asm volatile("s_waitcnt vmcnt(0)" ::: "memory");
;         __builtin_amdgcn_s_barrier();
;         asm volatile("" ::: "memory");
;         const int bprev = bcur == 0 ? 2 : bcur - 1, bnext = bcur == 2 ? 0 : bcur + 1;
;         if (kt + 1 < ntiles) MLA_STAGE(kt + 1, bnext);
;         if (late && kt >= 1 && kt - 1 <= wlast) mla_pv(lds + bprev * MLA_BUF, r, h, pf0, pf1, o);
.Lmla_toplate_0:
	s_cmp_eq_u32 s77, 0
	s_cbranch_scc1 .Lmla_stnow_0
	s_cmp_le_i32 s77, s84
	s_cbranch_scc0 .Lmla_stnow_0
	s_mul_i32 s89, s73, 0xac00
	s_add_i32 s90, s89, 0xffff5400
	s_cmp_lg_u32 s73, 0
	s_cselect_b32 s73, s90, 0x15800
	v_add_u32_e32 v0, s73, v182
	s_waitcnt vmcnt(0)
	s_barrier
	s_branch .Lmla_pvreads_0

; #define LAS __attribute__((address_space(3)))
; #define MFMA32(a, b, c) __builtin_amdgcn_mfma_f32_32x32x16_bf16((a), (b), (c), 0, 0, 0)
; DI void mla_pv(const LAS unsigned char* base, int r, int h, const bf16x8 (&pf0)[2], const bf16x8 (&pf1)[2], f32x16 (&o)[4]) {
;     const LAS unsigned char* vp = base + MLA_KBYTES + r * MLA_VROW + h * 32;
; #pragma unroll
;     for (int s = 0; s < 2; ++s) {
;         bf16x8 va[4], vb[4];
; #pragma unroll
;         for (int dt = 0; dt < 4; ++dt) { va[dt] = *(const LAS bf16x8*)(vp + dt * 32 * MLA_VROW + s * 16); vb[dt] = *(const LAS bf16x8*)(vp + dt * 32 * MLA_VROW + 64 + s * 16); }
;         __builtin_amdgcn_sched_barrier(0);
; #pragma unroll
;         for (int dt = 0; dt < 4; ++dt) o[dt] = MFMA32(va[dt], pf0[s], o[dt]);
; #pragma unroll
;         for (int dt = 0; dt < 4; ++dt) o[dt] = MFMA32(vb[dt], pf1[s], o[dt]);
;         __builtin_amdgcn_sched_barrier(0);
;     }
.Lmla_pvreads_0:
	ds_read_b128 v[84:87], v0 offset:25600
	ds_read_b128 v[88:91], v0 offset:25664
	ds_read_b128 v[92:95], v0 offset:30208
	ds_read_b128 v[96:99], v0 offset:30272
	ds_read_b128 v[100:103], v0 offset:34816
	ds_read_b128 v[104:107], v0 offset:34880
	ds_read_b128 v[108:111], v0 offset:39424
	ds_read_b128 v[186:189], v0 offset:39488
	ds_read_b128 v[200:203], v0 offset:25616
	ds_read_b128 v[204:207], v0 offset:25680
	ds_read_b128 v[208:211], v0 offset:30224
	ds_read_b128 v[212:215], v0 offset:30288
	ds_read_b128 v[216:219], v0 offset:34832
	ds_read_b128 v[220:223], v0 offset:34896
	ds_read_b128 v[224:227], v0 offset:39440
	ds_read_b128 v[228:231], v0 offset:39504
	s_cmp_ge_u32 s88, s74
	s_cbranch_scc1 .Lmla_pvplain_0
	s_mul_i32 s91, s76, 0xac00
	s_waitcnt lgkmcnt(8)
	v_mfma_f32_32x32x16_bf16 v[64:79], v[84:87], v[80:83], v[64:79]
	v_readlane_b32 s90, v255, 11
	v_lshl_add_u32 v253, s88, v176, v166
	s_add_i32 m0, s91, s90
	s_nop 0
	global_load_lds_dwordx4 v253, s[12:13]
	v_mfma_f32_32x32x16_bf16 v[48:63], v[92:95], v[80:83], v[48:63]
	v_mfma_f32_32x32x16_bf16 v[32:47], v[100:103], v[80:83], v[32:47]
	v_lshl_add_u32 v253, s88, v177, v167
	s_add_i32 m0, s91, s85
	s_nop 0
	global_load_lds_dwordx4 v253, s[12:13]
	v_mfma_f32_32x32x16_bf16 v[16:31], v[108:111], v[80:83], v[16:31]
	v_mfma_f32_32x32x16_bf16 v[64:79], v[88:91], v[6:9], v[64:79]
	v_lshl_add_u32 v253, s88, v178, v168
	s_add_i32 m0, s91, s72
	s_nop 0
	global_load_lds_dwordx4 v253, s[12:13]
	v_mfma_f32_32x32x16_bf16 v[48:63], v[96:99], v[6:9], v[48:63]
	v_mfma_f32_32x32x16_bf16 v[32:47], v[104:107], v[6:9], v[32:47]
	v_lshl_add_u32 v253, s88, v179, v169
	s_add_i32 m0, s91, s75
	s_nop 0
	global_load_lds_dwordx4 v253, s[12:13]
	v_mfma_f32_32x32x16_bf16 v[16:31], v[186:189], v[6:9], v[16:31]
	s_waitcnt lgkmcnt(0)
	v_mfma_f32_32x32x16_bf16 v[64:79], v[200:203], v[10:13], v[64:79]
	v_lshl_add_u32 v253, s88, v180, v170
	s_add_i32 m0, s91, s1
	s_nop 0
	global_load_lds_dwordx4 v253, s[12:13]
	v_mfma_f32_32x32x16_bf16 v[48:63], v[208:211], v[10:13], v[48:63]
	v_mfma_f32_32x32x16_bf16 v[32:47], v[216:219], v[10:13], v[32:47]
	s_andn2_b64 vcc, exec, s[94:95]
	s_cbranch_vccnz .Lmla_a5_pv_0
	v_readlane_b32 s90, v255, 9
	v_lshl_add_u32 v253, s88, v181, v171
	s_add_i32 m0, s91, s90
	s_nop 0
	global_load_lds_dwordx4 v253, s[12:13]

; DI void mla_block(const Params& p, LAS unsigned char* lds, int b, int hd, int qb, int tid) {
;     ...
;     for (int kt = 0; kt < ntiles; ++kt) {
;         asm volatile("s_waitcnt vmcnt(0)" ::: "memory");
;         __builtin_amdgcn_s_barrier();
;         asm volatile("" ::: "memory");
;         const int bprev = bcur == 0 ? 2 : bcur - 1, bnext = bcur == 2 ? 0 : bcur + 1;
;         if (kt + 1 < ntiles) MLA_STAGE(kt + 1, bnext);
;         if (late && kt >= 1 && kt - 1 <= wlast) mla_pv(lds + bprev * MLA_BUF, r, h, pf0, pf1, o);
.Lmla_toplate_1:
	s_cmp_eq_u32 s88, 0
	s_cbranch_scc1 .Lmla_stnow_1
	s_cmp_lt_i32 s100, s33
	s_cbranch_scc0 .Lmla_stnow_1
	s_mul_i32 s89, s87, 0xac00
	s_add_i32 s90, s89, 0xffff5400
	s_cmp_lg_u32 s87, 0
	s_cselect_b32 s87, s90, 0x15800
	v_add_u32_e32 v0, s87, v182
	s_waitcnt vmcnt(0)
	s_barrier
	s_branch .Lmla_pvreads_1

; #define LAS __attribute__((address_space(3)))
; #define MFMA32(a, b, c) __builtin_amdgcn_mfma_f32_32x32x16_bf16((a), (b), (c), 0, 0, 0)
; DI void mla_pv(const LAS unsigned char* base, int r, int h, const bf16x8 (&pf0)[2], const bf16x8 (&pf1)[2], f32x16 (&o)[4]) {
;     const LAS unsigned char* vp = base + MLA_KBYTES + r * MLA_VROW + h * 32;
; #pragma unroll
;     for (int s = 0; s < 2; ++s) {
;         bf16x8 va[4], vb[4];
; #pragma unroll
;         for (int dt = 0; dt < 4; ++dt) { va[dt] = *(const LAS bf16x8*)(vp + dt * 32 * MLA_VROW + s * 16); vb[dt] = *(const LAS bf16x8*)(vp + dt * 32 * MLA_VROW + 64 + s * 16); }
;         __builtin_amdgcn_sched_barrier(0);
; #pragma unroll
;         for (int dt = 0; dt < 4; ++dt) o[dt] = MFMA32(va[dt], pf0[s], o[dt]);
; #pragma unroll
;         for (int dt = 0; dt < 4; ++dt) o[dt] = MFMA32(vb[dt], pf1[s], o[dt]);
;         __builtin_amdgcn_sched_barrier(0);
;     }
.Lmla_pvreads_1:
	ds_read_b128 v[84:87], v0 offset:25600
	ds_read_b128 v[88:91], v0 offset:25664
	ds_read_b128 v[92:95], v0 offset:30208
	ds_read_b128 v[96:99], v0 offset:30272
	ds_read_b128 v[100:103], v0 offset:34816
	ds_read_b128 v[104:107], v0 offset:34880
	ds_read_b128 v[108:111], v0 offset:39424
	ds_read_b128 v[186:189], v0 offset:39488
	ds_read_b128 v[200:203], v0 offset:25616
	ds_read_b128 v[204:207], v0 offset:25680
	ds_read_b128 v[208:211], v0 offset:30224
	ds_read_b128 v[212:215], v0 offset:30288
	ds_read_b128 v[216:219], v0 offset:34832
	ds_read_b128 v[220:223], v0 offset:34896
	ds_read_b128 v[224:227], v0 offset:39440
	ds_read_b128 v[228:231], v0 offset:39504
	s_cmp_ge_u32 s77, s73
	s_cbranch_scc1 .Lmla_pvplain_1
	s_mul_i32 s91, s76, 0xac00
	s_waitcnt lgkmcnt(8)
	v_mfma_f32_32x32x16_bf16 v[64:79], v[84:87], v[80:83], v[64:79]
	v_readlane_b32 s90, v255, 9
	v_lshl_add_u32 v253, s98, v176, v166
	s_add_i32 m0, s91, s90
	s_nop 0
	global_load_lds_dwordx4 v253, s[12:13]
	v_mfma_f32_32x32x16_bf16 v[48:63], v[92:95], v[80:83], v[48:63]
	v_mfma_f32_32x32x16_bf16 v[32:47], v[100:103], v[80:83], v[32:47]
	v_lshl_add_u32 v253, s98, v177, v167
	s_add_i32 m0, s91, s75
	s_nop 0
	global_load_lds_dwordx4 v253, s[12:13]
	v_mfma_f32_32x32x16_bf16 v[16:31], v[108:111], v[80:83], v[16:31]
	v_mfma_f32_32x32x16_bf16 v[64:79], v[88:91], v[6:9], v[64:79]
	v_readlane_b32 s90, v255, 11
	v_lshl_add_u32 v253, s98, v178, v168
	s_add_i32 m0, s91, s90
	s_nop 0
	global_load_lds_dwordx4 v253, s[12:13]
	v_mfma_f32_32x32x16_bf16 v[48:63], v[96:99], v[6:9], v[48:63]
	v_mfma_f32_32x32x16_bf16 v[32:47], v[104:107], v[6:9], v[32:47]
	v_readlane_b32 s90, v255, 49
	v_lshl_add_u32 v253, s98, v179, v169
	s_add_i32 m0, s91, s90
	s_nop 0
	global_load_lds_dwordx4 v253, s[12:13]
	v_mfma_f32_32x32x16_bf16 v[16:31], v[186:189], v[6:9], v[16:31]
	s_waitcnt lgkmcnt(0)
	v_mfma_f32_32x32x16_bf16 v[64:79], v[200:203], v[10:13], v[64:79]
	v_lshl_add_u32 v253, s98, v180, v170
	s_add_i32 m0, s91, s86
	s_nop 0
	global_load_lds_dwordx4 v253, s[12:13]
	v_mfma_f32_32x32x16_bf16 v[48:63], v[208:211], v[10:13], v[48:63]
	v_mfma_f32_32x32x16_bf16 v[32:47], v[216:219], v[10:13], v[32:47]
	s_andn2_b64 vcc, exec, s[94:95]
	s_cbranch_vccnz .Lmla_a5_pv_1
	v_lshl_add_u32 v253, s98, v181, v171
	s_add_i32 m0, s91, s72
	s_nop 0
	global_load_lds_dwordx4 v253, s[12:13]
